# one static priority raise for waves 0-3 during each GEMM phase (no per-segment flips)
# speedup vs baseline: 1.0114x; 1.0008x over previous
; #define TID() int lane_v_; asm volatile("v_mbcnt_lo_u32_b32 %0, -1, 0\n\tv_mbcnt_hi_u32_b32 %0, -1, %0" : "=v"(lane_v_)); const int tid = wave_s * 64 + lane_v_
; #define PTRS() kptr_t kp = kargs(); unsigned char* ws = kws(kp); (void)ws
; __global__ void __launch_bounds__(NTHR, 2) hybrid_fwd(Args a) {
;     ...
;     if (IN(1)) for (int rep_ = 0; rep_ < REPS(1); ++rep_) { TID(); PTRS();
;         { pg8::Gemm g{S1, (const bf16_t*)(ws + WS_WQKVZ), M, ATT_IN, D}; pg8::StaticOrder S; S.init(M, ATT_IN, G, bid);
;           pg8::EpiQKVZ E{QKVZ, (const float*)(ws + WS_BIAS), (const float*)(ws + WS_COS), (const float*)(ws + WS_SIN)};
;           pg8::gemm_phase<pg8::EpiQKVZ, pg8::StaticOrder, true, true>(lds, g, S, E, tid); }
.LBB0_115:
	v_readlane_b32 s2, v254, 1
	v_readlane_b32 s3, v254, 2
	s_cmp_lt_i32 s2, 2
	s_cselect_b64 s[2:3], -1, 0
	s_and_b64 s[6:7], s[2:3], s[0:1]
	s_andn2_b64 vcc, exec, s[6:7]
	v_writelane_b32 v254, s52, 3
	s_cbranch_vccnz .LBB0_170
	v_readlane_b32 s98, v254, 3
	s_cmp_ge_u32 s98, 0x100
	s_cbranch_scc1 .Lmy_prio_1
	s_setprio 1

; __device__ __forceinline__ const float* kin(kptr_t p, int i) { return (const float*)(const GAS float*)*(const unsigned long long __attribute__((address_space(4)))*)(p + 8 * i); }
; #define TID() int lane_v_; asm volatile("v_mbcnt_lo_u32_b32 %0, -1, 0\n\tv_mbcnt_hi_u32_b32 %0, -1, %0" : "=v"(lane_v_)); const int tid = wave_s * 64 + lane_v_
; #define PTRS() kptr_t kp = kargs(); unsigned char* ws = kws(kp); (void)ws
; __global__ void __launch_bounds__(NTHR, 2) hybrid_fwd(Args a) {
;     ...
;     if (IN(3)) for (int rep_ = 0; rep_ < REPS(3); ++rep_) { TID(); PTRS();
;         pg8::Gemm g{S1, (const bf16_t*)(ws + WS_WO0), M, D, D}; pg8::StaticOrder S; S.init(M, D, G, bid);
;         pg8::EpiRes<false> E{(const void*)kin(kp, I_X), S3};
;         pg8::gemm_phase<pg8::EpiRes<false>, pg8::StaticOrder, true, true>(lds, g, S, E, tid);
.LBB0_302:
	v_readlane_b32 s2, v254, 1
	v_readlane_b32 s3, v254, 2
	s_cmp_lt_i32 s2, 4
	s_cselect_b64 s[2:3], -1, 0
	s_and_b64 s[4:5], s[2:3], s[0:1]
	s_andn2_b64 vcc, exec, s[4:5]
	s_cbranch_vccnz .LBB0_323
	v_readlane_b32 s98, v254, 3
	s_cmp_ge_u32 s98, 0x100
	s_cbranch_scc1 .Lmy_prio_3
	s_setprio 1

; #define TID() int lane_v_; asm volatile("v_mbcnt_lo_u32_b32 %0, -1, 0\n\tv_mbcnt_hi_u32_b32 %0, -1, %0" : "=v"(lane_v_)); const int tid = wave_s * 64 + lane_v_
; #define PTRS() kptr_t kp = kargs(); unsigned char* ws = kws(kp); (void)ws
; __global__ void __launch_bounds__(NTHR, 2) hybrid_fwd(Args a) {
;     ...
;     if (IN(4)) for (int rep_ = 0; rep_ < REPS(4); ++rep_) { TID(); PTRS();
;         pg8::Gemm g{S3, (const bf16_t*)(ws + WS_WG0), M, D, D}; pg8::StaticOrder S; S.init(M, D, G, bid);
;         pg8::EpiGate<false> E{S3, S2, (void*)S4};
;         pg8::gemm_phase<pg8::EpiGate<false>, pg8::StaticOrder, true, true>(lds, g, S, E, tid);
.LBB0_377:
	v_readlane_b32 s2, v254, 1
	v_readlane_b32 s3, v254, 2
	s_cmp_lt_i32 s2, 5
	s_cselect_b64 s[2:3], -1, 0
	s_and_b64 s[4:5], s[2:3], s[0:1]
	s_andn2_b64 vcc, exec, s[4:5]
	s_cbranch_vccnz .LBB0_398
	v_readlane_b32 s98, v254, 3
	s_cmp_ge_u32 s98, 0x100
	s_cbranch_scc1 .Lmy_prio_4
	s_setprio 1

; #define TID() int lane_v_; asm volatile("v_mbcnt_lo_u32_b32 %0, -1, 0\n\tv_mbcnt_hi_u32_b32 %0, -1, %0" : "=v"(lane_v_)); const int tid = wave_s * 64 + lane_v_
; #define PTRS() kptr_t kp = kargs(); unsigned char* ws = kws(kp); (void)ws
; __global__ void __launch_bounds__(NTHR, 2) hybrid_fwd(Args a) {
;     ...
;     if (IN(6)) for (int rep_ = 0; rep_ < REPS(6); ++rep_) { TID(); PTRS();
;         { pg8::Gemm g{XS0, WR, M, 2 * D, D, XS1, 4}; pg8::StaticOrder S; S.init(M, 2 * D, G, bid); S.wgm = 6; pg8::EpiStore2 E{S3, Kr, 4, D};
;           pg8::gemm_phase<pg8::EpiStore2, pg8::StaticOrder, true, true>(lds, g, S, E, tid); }
.LBB0_521:
	v_readlane_b32 s0, v254, 1
	v_readlane_b32 s1, v254, 2
	s_cmp_lt_i32 s0, 7
	s_cselect_b64 s[0:1], -1, 0
	s_and_b64 s[8:9], s[0:1], s[2:3]
	s_andn2_b64 vcc, exec, s[8:9]
	s_cbranch_vccnz .LBB0_562
	v_readlane_b32 s98, v254, 3
	s_cmp_ge_u32 s98, 0x100
	s_cbranch_scc1 .Lmy_prio_6
	s_setprio 1

; #define TID() int lane_v_; asm volatile("v_mbcnt_lo_u32_b32 %0, -1, 0\n\tv_mbcnt_hi_u32_b32 %0, -1, %0" : "=v"(lane_v_)); const int tid = wave_s * 64 + lane_v_
; #define PTRS() kptr_t kp = kargs(); unsigned char* ws = kws(kp); (void)ws
; __global__ void __launch_bounds__(NTHR, 2) hybrid_fwd(Args a) {
;     ...
;     if (IN(8)) for (int rep_ = 0; rep_ < REPS(8); ++rep_) { TID(); PTRS();
;         { pg8::Gemm g{XS0, WR + (size_t)2 * D * D, M, 2 * D, D, XS1, 4}; pg8::StaticOrder S; S.init(M, 2 * D, G, bid); S.wgm = 6; pg8::EpiStore2 E{Vr, S2, 4, D};
;           pg8::gemm_phase<pg8::EpiStore2, pg8::StaticOrder, true, true>(lds, g, S, E, tid); }
.LBB0_725:
	v_readlane_b32 s2, v254, 1
	v_readlane_b32 s3, v254, 2
	s_cmp_lt_i32 s2, 9
	s_cselect_b64 s[2:3], -1, 0
	s_and_b64 s[8:9], s[2:3], s[0:1]
	s_andn2_b64 vcc, exec, s[8:9]
	s_cbranch_vccnz .LBB0_746
	v_readlane_b32 s98, v254, 3
	s_cmp_ge_u32 s98, 0x100
	s_cbranch_scc1 .Lmy_prio_8
	s_setprio 1

; __device__ __forceinline__ const float* kin(kptr_t p, int i) { return (const float*)(const GAS float*)*(const unsigned long long __attribute__((address_space(4)))*)(p + 8 * i); }
; #define TID() int lane_v_; asm volatile("v_mbcnt_lo_u32_b32 %0, -1, 0\n\tv_mbcnt_hi_u32_b32 %0, -1, %0" : "=v"(lane_v_)); const int tid = wave_s * 64 + lane_v_
; #define PTRS() kptr_t kp = kargs(); unsigned char* ws = kws(kp); (void)ws
; __global__ void __launch_bounds__(NTHR, 2) hybrid_fwd(Args a) {
;     ...
;     if (IN(9)) for (int rep_ = 0; rep_ < REPS(9); ++rep_) { TID(); PTRS();
;         pg8::Gemm g{A2, (const bf16_t*)(ws + WS_W2), M, 2048, 128}; pg8::StaticOrder S; S.init(M, 2048, G, bid);
;         pg8::EpiWA E{WAb, kin(kp, I_W0), kin(kp, I_A0)};
;         pg8::gemm_phase<pg8::EpiWA, pg8::StaticOrder, true, true>(lds, g, S, E, tid);
.LBB0_800:
	v_readlane_b32 s2, v254, 1
	v_readlane_b32 s3, v254, 2
	s_cmp_lt_i32 s2, 10
	s_cselect_b64 s[2:3], -1, 0
	s_and_b64 s[4:5], s[2:3], s[0:1]
	s_andn2_b64 vcc, exec, s[4:5]
	s_cbranch_vccnz .LBB0_819
	v_readlane_b32 s98, v254, 3
	s_cmp_ge_u32 s98, 0x100
	s_cbranch_scc1 .Lmy_prio_9
	s_setprio 1

; #define TID() int lane_v_; asm volatile("v_mbcnt_lo_u32_b32 %0, -1, 0\n\tv_mbcnt_hi_u32_b32 %0, -1, %0" : "=v"(lane_v_)); const int tid = wave_s * 64 + lane_v_
; #define PTRS() kptr_t kp = kargs(); unsigned char* ws = kws(kp); (void)ws
; __global__ void __launch_bounds__(NTHR, 2) hybrid_fwd(Args a) {
;     ...
;     if (IN(12)) for (int rep_ = 0; rep_ < REPS(12); ++rep_) { TID(); PTRS();
;         { pg8::Gemm g{S1, (const bf16_t*)(ws + WS_WO1), M, D, D}; pg8::StaticOrder S; S.init(M, D, G, bid); pg8::EpiRes<true> E{(const void*)S4, S3};
;           pg8::gemm_phase<pg8::EpiRes<true>, pg8::StaticOrder, true, true>(lds, g, S, E, tid); }
.LBB0_1066:
	v_readlane_b32 s2, v254, 1
	v_readlane_b32 s3, v254, 2
	s_cmp_lt_i32 s2, 13
	s_cselect_b64 s[2:3], -1, 0
	s_and_b64 s[4:5], s[2:3], s[0:1]
	s_andn2_b64 vcc, exec, s[4:5]
	s_cbranch_vccnz .LBB0_1107
	v_readlane_b32 s98, v254, 3
	s_cmp_ge_u32 s98, 0x100
	s_cbranch_scc1 .Lmy_prio_12
	s_setprio 1

; #define TID() int lane_v_; asm volatile("v_mbcnt_lo_u32_b32 %0, -1, 0\n\tv_mbcnt_hi_u32_b32 %0, -1, %0" : "=v"(lane_v_)); const int tid = wave_s * 64 + lane_v_
; #define PTRS() kptr_t kp = kargs(); unsigned char* ws = kws(kp); (void)ws
; __global__ void __launch_bounds__(NTHR, 2) hybrid_fwd(Args a) {
;     ...
;     if (IN(13)) for (int rep_ = 0; rep_ < REPS(13); ++rep_) { TID(); PTRS();
;         pg8::Gemm g{S3, (const bf16_t*)(ws + WS_WG1), M, D, D}; pg8::StaticOrder S; S.init(M, D, G, bid);
;         pg8::EpiGate<false> E{S3, S2, (void*)S1};
;         pg8::gemm_phase<pg8::EpiGate<false>, pg8::StaticOrder, true, true>(lds, g, S, E, tid);
.LBB0_1161:
	v_readlane_b32 s2, v254, 1
	v_readlane_b32 s3, v254, 2
	s_cmp_lt_i32 s2, 14
	s_cselect_b64 s[2:3], -1, 0
	s_and_b64 s[4:5], s[2:3], s[0:1]
	s_andn2_b64 vcc, exec, s[4:5]
	s_cbranch_vccnz .LBB0_1182
	v_readlane_b32 s98, v254, 3
	s_cmp_ge_u32 s98, 0x100
	s_cbranch_scc1 .Lmy_prio_13
	s_setprio 1
